# scan: v vector of each 4-step group prefetched one group ahead into alternating register quads; relaxed the lgkmcnt wait that exposed its LDS latency
# speedup vs baseline: 1.0049x; 1.0049x over previous
; template <int CTRL> DI float dppf(float v) { return __int_as_float(__builtin_amdgcn_update_dpp(0, __float_as_int(v), CTRL, 0xf, 0xf, false)); }
; DI float red16(float p) { p += dppf<0xB1>(p); p += dppf<0x4E>(p); p += dppf<0x141>(p); p += dppf<0x140>(p); return p; }
; DI void scan_task(const Params& P, int sb, unsigned char* lds) {
;     ...
;       const float* cb = buf + (c & 1) * (CH * SREC);
;       const float* vrow = vtb + (c & 1) * (16 * CH) + rowl * CH;
;       float* yb = ybuf + (c & 1) * (CH * 16);
;       StepOps cur, nxt, nx2, nx3;
;       ld_ops(cur, cb, q4);
;       ld_ops(nxt, cb + SREC, q4);
;       ld_ops(nx2, cb + 2 * SREC, q4);
; #pragma unroll 1
;       for (int g4 = 0; g4 < CH / 4; ++g4) {
;         const float* gb = cb + g4 * 4 * SREC;
;         const float4 v4 = *(const float4*)(vrow + g4 * 4);
;         float pp[4];
; #pragma unroll
;         for (int i = 0; i < 4; ++i) {
;           ld_ops(nx3, gb + (i + 3) * SREC, q4);
;           const f2 a01 = {cur.a.x, cur.a.y}, a23 = {cur.a.z, cur.a.w}, w01 = {cur.w.x, cur.w.y}, w23 = {cur.w.z, cur.w.w};
;           const f2 k01 = {cur.k.x, cur.k.y}, k23 = {cur.k.z, cur.k.w}, b01 = {cur.b.x, cur.b.y}, b23 = {cur.b.z, cur.b.w};
;           const f2 r01 = {cur.r.x, cur.r.y}, r23 = {cur.r.z, cur.r.w};
;           f2 pa = S0 * a01; pa += S1 * a23;
;           const float vs = (i == 0) ? v4.x : (i == 1) ? v4.y : (i == 2) ? v4.z : v4.w;
;           const f2 vv = {vs, vs};
;           const f2 t0 = S0 * w01 + vv * k01, t1 = S1 * w23 + vv * k23;
;           const float sa = red16(pa.x + pa.y);
;           const f2 sa2 = {sa, sa};
;           S0 = t0 + sa2 * b01; S1 = t1 + sa2 * b23;
;           f2 py = S0 * r01; py += S1 * r23;
;           pp[i] = py.x + py.y;
;           cur = nxt; nxt = nx2; nx2 = nx3;
;         }
;         const float tA = o1 ? pp[0] : pp[1], kA = o1 ? pp[1] : pp[0];
;         const float tB = o1 ? pp[2] : pp[3], kB = o1 ? pp[3] : pp[2];
;         const float r0 = kA + dppf<0xB1>(tA), r1 = kB + dppf<0xB1>(tB);
;         const float tC = o2 ? r0 : r1, kC = o2 ? r1 : r0;
;         float u = kC + dppf<0x4E>(tC);
;         u += dppf<0x124>(u);
;         u += dppf<0x128>(u);
;         yb[(g4 * 4 + (q & 3)) * 16 + rowl] = u;
.LBB0_1197:
	s_and_b32 s3, s0, 1
	s_lshl_b32 s2, s3, 11
	s_mul_i32 s3, s3, 0xb000
	v_lshl_or_b32 v56, v68, 2, s3
	v_add_u32_e32 v72, s3, v69
	v_or_b32_e32 v74, s2, v71
	v_add_u32_e32 v100, 0x18000, v74
	ds_read_b128 v[88:91], v100
	ds_read_b128 v[0:3], v56
	ds_read_b128 v[4:7], v56 offset:256
	s_waitcnt vmcnt(1)
	ds_read_b128 v[8:11], v56 offset:512
	ds_read_b128 v[12:15], v56 offset:768
	ds_read_b128 v[16:19], v56 offset:1024
	ds_read_b128 v[20:23], v56 offset:1408
	ds_read_b128 v[24:27], v56 offset:1664
	ds_read_b128 v[36:39], v56 offset:1920
	ds_read_b128 v[28:31], v56 offset:2176
	ds_read_b128 v[32:35], v56 offset:2432
	ds_read_b128 v[40:43], v56 offset:2816
	ds_read_b128 v[44:47], v56 offset:3072
	ds_read_b128 v[48:51], v56 offset:3328
	ds_read_b128 v[52:55], v56 offset:3584
	ds_read_b128 v[56:59], v56 offset:3840
	v_add_u32_e32 v73, s2, v70
	s_mov_b32 s3, 8
.LBB0_1198:
	s_waitcnt lgkmcnt(14)
	v_pk_mul_f32 v[2:3], v[64:65], v[2:3]
	ds_read_b128 v[60:63], v72 offset:256
	ds_read_b128 v[76:79], v72 offset:512
	ds_read_b128 v[80:83], v72 offset:768
	ds_read_b128 v[84:87], v72 offset:1024
	ds_read_b128 v[112:115], v100 offset:16
	ds_read_b128 v[92:95], v72
	v_pk_fma_f32 v[96:97], v[66:67], v[0:1], v[2:3]
	ds_read_b128 v[0:3], v72 offset:1408
	v_add_f32_e32 v75, v96, v97
	s_waitcnt lgkmcnt(7)
	v_pk_mul_f32 v[14:15], v[14:15], v[88:89] op_sel_hi:[1,0]
	v_pk_mul_f32 v[12:13], v[12:13], v[88:89] op_sel_hi:[1,0]
	v_add_f32_dpp v75, v75, v75 quad_perm:[1,0,3,2] row_mask:0xf bank_mask:0xf bound_ctrl:1
	v_pk_fma_f32 v[64:65], v[64:65], v[10:11], v[14:15]
	v_pk_fma_f32 v[66:67], v[66:67], v[8:9], v[12:13]
	v_add_f32_dpp v75, v75, v75 quad_perm:[2,3,0,1] row_mask:0xf bank_mask:0xf bound_ctrl:1
	v_mov_b32_e32 v98, v91
	ds_read_b128 v[8:11], v72 offset:1920
	ds_read_b128 v[12:15], v72 offset:2176
	v_add_f32_dpp v75, v75, v75 row_half_mirror row_mask:0xf bank_mask:0xf bound_ctrl:1
	s_nop 1
	v_add_f32_dpp v96, v75, v75 row_mirror row_mask:0xf bank_mask:0xf bound_ctrl:1
	v_pk_fma_f32 v[64:65], v[6:7], v[96:97], v[64:65] op_sel_hi:[1,0,1]
	v_pk_fma_f32 v[66:67], v[4:5], v[96:97], v[66:67] op_sel_hi:[1,0,1]
	v_pk_mul_f32 v[18:19], v[18:19], v[64:65]
	v_pk_mul_f32 v[22:23], v[22:23], v[64:65]
	v_pk_mul_f32 v[36:37], v[36:37], v[66:67]
	v_pk_mul_f32 v[38:39], v[38:39], v[64:65]
	v_pk_fma_f32 v[64:65], v[16:17], v[66:67], v[18:19]
	v_pk_fma_f32 v[66:67], v[20:21], v[66:67], v[22:23]
	v_add_f32_e32 v75, v64, v65
	v_add_f32_e32 v64, v66, v67
	v_pk_fma_f32 v[36:37], v[28:29], v[88:89], v[36:37] op_sel:[0,1,0]
	v_pk_fma_f32 v[38:39], v[30:31], v[88:89], v[38:39] op_sel:[0,1,0]
	v_add_f32_dpp v64, v64, v64 quad_perm:[1,0,3,2] row_mask:0xf bank_mask:0xf bound_ctrl:1
	ds_read_b128 v[4:7], v72 offset:1664
	ds_read_b128 v[16:19], v72 offset:2432
	v_add_f32_dpp v64, v64, v64 quad_perm:[2,3,0,1] row_mask:0xf bank_mask:0xf bound_ctrl:1
	ds_read_b128 v[20:23], v72 offset:2816
	ds_read_b128 v[28:31], v72 offset:3584
	v_add_f32_dpp v64, v64, v64 row_half_mirror row_mask:0xf bank_mask:0xf bound_ctrl:1
	s_nop 1
	v_add_f32_dpp v64, v64, v64 row_mirror row_mask:0xf bank_mask:0xf bound_ctrl:1
	v_pk_fma_f32 v[66:67], v[24:25], v[64:65], v[36:37] op_sel_hi:[1,0,1]
	v_pk_fma_f32 v[64:65], v[26:27], v[64:65], v[38:39] op_sel_hi:[1,0,1]
	v_pk_mul_f32 v[88:89], v[48:49], v[66:67]
	v_pk_mul_f32 v[34:35], v[34:35], v[64:65]
	v_pk_mul_f32 v[42:43], v[42:43], v[64:65]
	v_pk_fma_f32 v[96:97], v[32:33], v[66:67], v[34:35]
	v_pk_fma_f32 v[66:67], v[40:41], v[66:67], v[42:43]
	v_pk_mul_f32 v[64:65], v[50:51], v[64:65]
	v_add_f32_e32 v66, v66, v67
	v_pk_fma_f32 v[88:89], v[52:53], v[90:91], v[88:89] op_sel_hi:[1,0,1]
	v_pk_fma_f32 v[64:65], v[54:55], v[90:91], v[64:65] op_sel_hi:[1,0,1]
	v_add_f32_dpp v66, v66, v66 quad_perm:[1,0,3,2] row_mask:0xf bank_mask:0xf bound_ctrl:1
	v_add_f32_e32 v90, v96, v97
	v_add_f32_dpp v105, v75, v75 row_ror:8 row_mask:0xf bank_mask:0x3 bound_ctrl:1
	v_add_f32_dpp v66, v66, v66 quad_perm:[2,3,0,1] row_mask:0xf bank_mask:0xf bound_ctrl:1
	v_add_f32_dpp v107, v90, v90 row_ror:8 row_mask:0xf bank_mask:0x3 bound_ctrl:1
	ds_read_b128 v[24:27], v72 offset:3072
	ds_read_b128 v[36:39], v72 offset:3328
	v_add_f32_dpp v66, v66, v66 row_half_mirror row_mask:0xf bank_mask:0xf bound_ctrl:1
	ds_read_b128 v[48:51], v72 offset:4736
	ds_read_b128 v[32:35], v72 offset:3840
	v_add_f32_dpp v66, v66, v66 row_mirror row_mask:0xf bank_mask:0xf bound_ctrl:1
	v_pk_fma_f32 v[64:65], v[46:47], v[66:67], v[64:65] op_sel_hi:[1,0,1]
	v_pk_fma_f32 v[88:89], v[44:45], v[66:67], v[88:89] op_sel_hi:[1,0,1]
	s_waitcnt lgkmcnt(11)
	v_pk_mul_f32 v[66:67], v[94:95], v[64:65]
	v_pk_mul_f32 v[58:59], v[58:59], v[64:65]
	v_pk_fma_f32 v[66:67], v[92:93], v[88:89], v[66:67]
	v_pk_mul_f32 v[64:65], v[78:79], v[64:65]
	v_add_f32_e32 v66, v66, v67
	v_pk_fma_f32 v[78:79], v[56:57], v[88:89], v[58:59]
	v_pk_mul_f32 v[76:77], v[76:77], v[88:89]
	v_add_f32_dpp v66, v66, v66 quad_perm:[1,0,3,2] row_mask:0xf bank_mask:0xf bound_ctrl:1
	v_pk_fma_f32 v[64:65], v[98:99], v[82:83], v[64:65] op_sel_hi:[0,1,1]
	v_add_f32_e32 v104, v78, v79
	v_add_f32_dpp v66, v66, v66 quad_perm:[2,3,0,1] row_mask:0xf bank_mask:0xf bound_ctrl:1
	v_pk_fma_f32 v[76:77], v[98:99], v[80:81], v[76:77] op_sel_hi:[0,1,1]
	ds_read_b128 v[40:43], v72 offset:4224
	ds_read_b128 v[52:55], v72 offset:4992
	v_add_f32_dpp v66, v66, v66 row_half_mirror row_mask:0xf bank_mask:0xf bound_ctrl:1
	ds_read_b128 v[44:47], v72 offset:4480
	ds_read_b128 v[56:59], v72 offset:5248
	v_add_f32_dpp v78, v66, v66 row_mirror row_mask:0xf bank_mask:0xf bound_ctrl:1
	v_pk_fma_f32 v[64:65], v[62:63], v[78:79], v[64:65] op_sel_hi:[1,0,1]
	v_pk_fma_f32 v[66:67], v[60:61], v[78:79], v[76:77] op_sel_hi:[1,0,1]
	v_pk_mul_f32 v[102:103], v[86:87], v[64:65]
	v_pk_fma_f32 v[102:103], v[84:85], v[66:67], v[102:103]
	s_waitcnt lgkmcnt(14)
; template <int CTRL> DI float dppf(float v) { return __int_as_float(__builtin_amdgcn_update_dpp(0, __float_as_int(v), CTRL, 0xf, 0xf, false)); }
; DI float red16(float p) { p += dppf<0xB1>(p); p += dppf<0x4E>(p); p += dppf<0x141>(p); p += dppf<0x140>(p); return p; }
; DI void scan_task(const Params& P, int sb, unsigned char* lds) {
;     ...
;       for (int g4 = 0; g4 < CH / 4; ++g4) {
;         const float* gb = cb + g4 * 4 * SREC;
;         const float4 v4 = *(const float4*)(vrow + g4 * 4);
;         float pp[4];
; #pragma unroll
;         for (int i = 0; i < 4; ++i) {
;           ld_ops(nx3, gb + (i + 3) * SREC, q4);
;           const f2 a01 = {cur.a.x, cur.a.y}, a23 = {cur.a.z, cur.a.w}, w01 = {cur.w.x, cur.w.y}, w23 = {cur.w.z, cur.w.w};
;           const f2 k01 = {cur.k.x, cur.k.y}, k23 = {cur.k.z, cur.k.w}, b01 = {cur.b.x, cur.b.y}, b23 = {cur.b.z, cur.b.w};
;           const f2 r01 = {cur.r.x, cur.r.y}, r23 = {cur.r.z, cur.r.w};
;           f2 pa = S0 * a01; pa += S1 * a23;
;           const float vs = (i == 0) ? v4.x : (i == 1) ? v4.y : (i == 2) ? v4.z : v4.w;
;           const f2 vv = {vs, vs};
;           const f2 t0 = S0 * w01 + vv * k01, t1 = S1 * w23 + vv * k23;
;           const float sa = red16(pa.x + pa.y);
;           const f2 sa2 = {sa, sa};
;           S0 = t0 + sa2 * b01; S1 = t1 + sa2 * b23;
;           f2 py = S0 * r01; py += S1 * r23;
;           pp[i] = py.x + py.y;
;           cur = nxt; nxt = nx2; nx2 = nx3;
;         }
;         const float tA = o1 ? pp[0] : pp[1], kA = o1 ? pp[1] : pp[0];
;         const float tB = o1 ? pp[2] : pp[3], kB = o1 ? pp[3] : pp[2];
;         const float r0 = kA + dppf<0xB1>(tA), r1 = kB + dppf<0xB1>(tB);
;         const float tC = o2 ? r0 : r1, kC = o2 ? r1 : r0;
;         float u = kC + dppf<0x4E>(tC);
;         u += dppf<0x124>(u);
;         u += dppf<0x128>(u);
;         yb[(g4 * 4 + (q & 3)) * 16 + rowl] = u;
	v_pk_mul_f32 v[2:3], v[64:65], v[2:3]
	v_add_f32_e32 v102, v102, v103
	ds_read_b128 v[60:63], v72 offset:5888
	v_add_f32_dpp v105, v104, v104 row_ror:8 row_mask:0xf bank_mask:0xc bound_ctrl:1
	ds_read_b128 v[76:79], v72 offset:6144
	ds_read_b128 v[80:83], v72 offset:6400
	ds_read_b128 v[84:87], v72 offset:6656
	ds_read_b128 v[88:91], v100 offset:32
	ds_read_b128 v[92:95], v72 offset:5632
	v_add_f32_dpp v107, v102, v102 row_ror:8 row_mask:0xf bank_mask:0xc bound_ctrl:1
	v_pk_fma_f32 v[96:97], v[66:67], v[0:1], v[2:3]
	v_add_f32_dpp v108, v105, v105 row_half_mirror row_mask:0xf bank_mask:0x5 bound_ctrl:1
	v_add_f32_dpp v108, v107, v107 row_half_mirror row_mask:0xf bank_mask:0xa bound_ctrl:1
	ds_read_b128 v[0:3], v72 offset:7040
	v_add_f32_e32 v75, v96, v97
	s_waitcnt lgkmcnt(7)
	v_add_f32_dpp v108, v108, v108 quad_perm:[1,0,3,2] row_mask:0xf bank_mask:0xf bound_ctrl:1
	v_pk_mul_f32 v[14:15], v[14:15], v[112:113] op_sel_hi:[1,0]
	v_pk_mul_f32 v[12:13], v[12:13], v[112:113] op_sel_hi:[1,0]
	v_add_f32_dpp v108, v108, v108 quad_perm:[2,3,0,1] row_mask:0xf bank_mask:0xf bound_ctrl:1
	v_add_f32_dpp v75, v75, v75 quad_perm:[1,0,3,2] row_mask:0xf bank_mask:0xf bound_ctrl:1
	v_pk_fma_f32 v[64:65], v[64:65], v[10:11], v[14:15]
	v_pk_fma_f32 v[66:67], v[66:67], v[8:9], v[12:13]
	v_add_f32_dpp v75, v75, v75 quad_perm:[2,3,0,1] row_mask:0xf bank_mask:0xf bound_ctrl:1
	v_mov_b32_e32 v98, v115
	ds_write_b32 v73, v108
	v_add_f32_dpp v75, v75, v75 row_half_mirror row_mask:0xf bank_mask:0xf bound_ctrl:1
	ds_read_b128 v[8:11], v72 offset:7552
	ds_read_b128 v[12:15], v72 offset:7808
	v_add_f32_dpp v96, v75, v75 row_mirror row_mask:0xf bank_mask:0xf bound_ctrl:1
	v_pk_fma_f32 v[64:65], v[6:7], v[96:97], v[64:65] op_sel_hi:[1,0,1]
	v_pk_fma_f32 v[66:67], v[4:5], v[96:97], v[66:67] op_sel_hi:[1,0,1]
	v_pk_mul_f32 v[18:19], v[18:19], v[64:65]
	v_pk_mul_f32 v[22:23], v[22:23], v[64:65]
	v_pk_mul_f32 v[36:37], v[36:37], v[66:67]
	v_pk_mul_f32 v[38:39], v[38:39], v[64:65]
	v_pk_fma_f32 v[64:65], v[16:17], v[66:67], v[18:19]
	v_pk_fma_f32 v[66:67], v[20:21], v[66:67], v[22:23]
	v_add_f32_e32 v75, v64, v65
	v_add_f32_e32 v64, v66, v67
	v_pk_fma_f32 v[36:37], v[28:29], v[112:113], v[36:37] op_sel:[0,1,0]
	v_pk_fma_f32 v[38:39], v[30:31], v[112:113], v[38:39] op_sel:[0,1,0]
	v_add_f32_dpp v64, v64, v64 quad_perm:[1,0,3,2] row_mask:0xf bank_mask:0xf bound_ctrl:1
	ds_read_b128 v[4:7], v72 offset:7296
	ds_read_b128 v[16:19], v72 offset:8064
	v_add_f32_dpp v64, v64, v64 quad_perm:[2,3,0,1] row_mask:0xf bank_mask:0xf bound_ctrl:1
	ds_read_b128 v[20:23], v72 offset:8448
	ds_read_b128 v[28:31], v72 offset:9216
	v_add_f32_dpp v64, v64, v64 row_half_mirror row_mask:0xf bank_mask:0xf bound_ctrl:1
	s_nop 1
	v_add_f32_dpp v64, v64, v64 row_mirror row_mask:0xf bank_mask:0xf bound_ctrl:1
	v_pk_fma_f32 v[66:67], v[24:25], v[64:65], v[36:37] op_sel_hi:[1,0,1]
	v_pk_fma_f32 v[64:65], v[26:27], v[64:65], v[38:39] op_sel_hi:[1,0,1]
	v_pk_mul_f32 v[112:113], v[48:49], v[66:67]
	v_pk_mul_f32 v[34:35], v[34:35], v[64:65]
	v_pk_mul_f32 v[42:43], v[42:43], v[64:65]
	v_pk_fma_f32 v[96:97], v[32:33], v[66:67], v[34:35]
	v_pk_fma_f32 v[66:67], v[40:41], v[66:67], v[42:43]
	v_pk_mul_f32 v[64:65], v[50:51], v[64:65]
	v_add_f32_e32 v66, v66, v67
	v_pk_fma_f32 v[112:113], v[52:53], v[114:115], v[112:113] op_sel_hi:[1,0,1]
	v_pk_fma_f32 v[64:65], v[54:55], v[114:115], v[64:65] op_sel_hi:[1,0,1]
	v_add_f32_dpp v66, v66, v66 quad_perm:[1,0,3,2] row_mask:0xf bank_mask:0xf bound_ctrl:1
	v_add_f32_e32 v114, v96, v97
	v_add_f32_dpp v105, v75, v75 row_ror:8 row_mask:0xf bank_mask:0x3 bound_ctrl:1
	v_add_f32_dpp v66, v66, v66 quad_perm:[2,3,0,1] row_mask:0xf bank_mask:0xf bound_ctrl:1
	v_add_f32_dpp v107, v114, v114 row_ror:8 row_mask:0xf bank_mask:0x3 bound_ctrl:1
	ds_read_b128 v[24:27], v72 offset:8704
	ds_read_b128 v[36:39], v72 offset:8960
	v_add_f32_dpp v66, v66, v66 row_half_mirror row_mask:0xf bank_mask:0xf bound_ctrl:1
	ds_read_b128 v[48:51], v72 offset:10368
	ds_read_b128 v[32:35], v72 offset:9472
	v_add_f32_dpp v66, v66, v66 row_mirror row_mask:0xf bank_mask:0xf bound_ctrl:1
	v_pk_fma_f32 v[64:65], v[46:47], v[66:67], v[64:65] op_sel_hi:[1,0,1]
	v_pk_fma_f32 v[112:113], v[44:45], v[66:67], v[112:113] op_sel_hi:[1,0,1]
	s_waitcnt lgkmcnt(11)
	v_pk_mul_f32 v[66:67], v[94:95], v[64:65]
	v_pk_mul_f32 v[58:59], v[58:59], v[64:65]
	v_pk_fma_f32 v[66:67], v[92:93], v[112:113], v[66:67]
	v_pk_mul_f32 v[64:65], v[78:79], v[64:65]
	v_add_f32_e32 v66, v66, v67
	v_pk_fma_f32 v[78:79], v[56:57], v[112:113], v[58:59]
	v_pk_mul_f32 v[76:77], v[76:77], v[112:113]
	v_add_f32_dpp v66, v66, v66 quad_perm:[1,0,3,2] row_mask:0xf bank_mask:0xf bound_ctrl:1
	v_pk_fma_f32 v[64:65], v[98:99], v[82:83], v[64:65] op_sel_hi:[0,1,1]
	v_add_f32_e32 v104, v78, v79
	v_add_f32_dpp v66, v66, v66 quad_perm:[2,3,0,1] row_mask:0xf bank_mask:0xf bound_ctrl:1
	v_pk_fma_f32 v[76:77], v[98:99], v[80:81], v[76:77] op_sel_hi:[0,1,1]
	ds_read_b128 v[40:43], v72 offset:9856
	ds_read_b128 v[52:55], v72 offset:10624
	v_add_f32_dpp v66, v66, v66 row_half_mirror row_mask:0xf bank_mask:0xf bound_ctrl:1
	ds_read_b128 v[44:47], v72 offset:10112
	ds_read_b128 v[56:59], v72 offset:10880
	v_add_f32_dpp v78, v66, v66 row_mirror row_mask:0xf bank_mask:0xf bound_ctrl:1
	v_pk_fma_f32 v[64:65], v[62:63], v[78:79], v[64:65] op_sel_hi:[1,0,1]
	v_pk_fma_f32 v[66:67], v[60:61], v[78:79], v[76:77] op_sel_hi:[1,0,1]
	v_pk_mul_f32 v[102:103], v[86:87], v[64:65]
	v_pk_fma_f32 v[102:103], v[84:85], v[66:67], v[102:103]
	s_waitcnt lgkmcnt(14)
; template <int CTRL> DI float dppf(float v) { return __int_as_float(__builtin_amdgcn_update_dpp(0, __float_as_int(v), CTRL, 0xf, 0xf, false)); }
; DI float red16(float p) { p += dppf<0xB1>(p); p += dppf<0x4E>(p); p += dppf<0x141>(p); p += dppf<0x140>(p); return p; }
; DI void scan_task(const Params& P, int sb, unsigned char* lds) {
;     ...
;       for (int g4 = 0; g4 < CH / 4; ++g4) {
;         const float* gb = cb + g4 * 4 * SREC;
;         const float4 v4 = *(const float4*)(vrow + g4 * 4);
;         float pp[4];
; #pragma unroll
;         for (int i = 0; i < 4; ++i) {
;           ld_ops(nx3, gb + (i + 3) * SREC, q4);
;           const f2 a01 = {cur.a.x, cur.a.y}, a23 = {cur.a.z, cur.a.w}, w01 = {cur.w.x, cur.w.y}, w23 = {cur.w.z, cur.w.w};
;           const f2 k01 = {cur.k.x, cur.k.y}, k23 = {cur.k.z, cur.k.w}, b01 = {cur.b.x, cur.b.y}, b23 = {cur.b.z, cur.b.w};
;           const f2 r01 = {cur.r.x, cur.r.y}, r23 = {cur.r.z, cur.r.w};
;           f2 pa = S0 * a01; pa += S1 * a23;
;           const float vs = (i == 0) ? v4.x : (i == 1) ? v4.y : (i == 2) ? v4.z : v4.w;
;           const f2 vv = {vs, vs};
;           const f2 t0 = S0 * w01 + vv * k01, t1 = S1 * w23 + vv * k23;
;           const float sa = red16(pa.x + pa.y);
;           const f2 sa2 = {sa, sa};
;           S0 = t0 + sa2 * b01; S1 = t1 + sa2 * b23;
;           f2 py = S0 * r01; py += S1 * r23;
;           pp[i] = py.x + py.y;
;           cur = nxt; nxt = nx2; nx2 = nx3;
;         }
;         const float tA = o1 ? pp[0] : pp[1], kA = o1 ? pp[1] : pp[0];
;         const float tB = o1 ? pp[2] : pp[3], kB = o1 ? pp[3] : pp[2];
;         const float r0 = kA + dppf<0xB1>(tA), r1 = kB + dppf<0xB1>(tB);
;         const float tC = o2 ? r0 : r1, kC = o2 ? r1 : r0;
;         float u = kC + dppf<0x4E>(tC);
;         u += dppf<0x124>(u);
;         u += dppf<0x128>(u);
;         yb[(g4 * 4 + (q & 3)) * 16 + rowl] = u;
	v_pk_mul_f32 v[2:3], v[64:65], v[2:3]
	v_add_f32_e32 v102, v102, v103
	ds_read_b128 v[60:63], v72 offset:11520
	v_add_f32_dpp v105, v104, v104 row_ror:8 row_mask:0xf bank_mask:0xc bound_ctrl:1
	ds_read_b128 v[76:79], v72 offset:11776
	ds_read_b128 v[80:83], v72 offset:12032
	ds_read_b128 v[84:87], v72 offset:12288
	ds_read_b128 v[112:115], v100 offset:48
	ds_read_b128 v[92:95], v72 offset:11264
	v_add_f32_dpp v107, v102, v102 row_ror:8 row_mask:0xf bank_mask:0xc bound_ctrl:1
	v_pk_fma_f32 v[96:97], v[66:67], v[0:1], v[2:3]
	v_add_f32_dpp v108, v105, v105 row_half_mirror row_mask:0xf bank_mask:0x5 bound_ctrl:1
	v_add_f32_dpp v108, v107, v107 row_half_mirror row_mask:0xf bank_mask:0xa bound_ctrl:1
	ds_read_b128 v[0:3], v72 offset:12672
	v_add_f32_e32 v75, v96, v97
	s_waitcnt lgkmcnt(7)
	v_add_f32_dpp v108, v108, v108 quad_perm:[1,0,3,2] row_mask:0xf bank_mask:0xf bound_ctrl:1
	v_pk_mul_f32 v[14:15], v[14:15], v[88:89] op_sel_hi:[1,0]
	v_pk_mul_f32 v[12:13], v[12:13], v[88:89] op_sel_hi:[1,0]
	v_add_f32_dpp v108, v108, v108 quad_perm:[2,3,0,1] row_mask:0xf bank_mask:0xf bound_ctrl:1
	v_add_f32_dpp v75, v75, v75 quad_perm:[1,0,3,2] row_mask:0xf bank_mask:0xf bound_ctrl:1
	v_pk_fma_f32 v[64:65], v[64:65], v[10:11], v[14:15]
	v_pk_fma_f32 v[66:67], v[66:67], v[8:9], v[12:13]
	v_add_f32_dpp v75, v75, v75 quad_perm:[2,3,0,1] row_mask:0xf bank_mask:0xf bound_ctrl:1
	v_mov_b32_e32 v98, v91
	ds_write_b32 v73, v108 offset:256
	v_add_f32_dpp v75, v75, v75 row_half_mirror row_mask:0xf bank_mask:0xf bound_ctrl:1
	ds_read_b128 v[8:11], v72 offset:13184
	ds_read_b128 v[12:15], v72 offset:13440
	v_add_f32_dpp v96, v75, v75 row_mirror row_mask:0xf bank_mask:0xf bound_ctrl:1
	v_pk_fma_f32 v[64:65], v[6:7], v[96:97], v[64:65] op_sel_hi:[1,0,1]
	v_pk_fma_f32 v[66:67], v[4:5], v[96:97], v[66:67] op_sel_hi:[1,0,1]
	v_pk_mul_f32 v[18:19], v[18:19], v[64:65]
	v_pk_mul_f32 v[22:23], v[22:23], v[64:65]
	v_pk_mul_f32 v[36:37], v[36:37], v[66:67]
	v_pk_mul_f32 v[38:39], v[38:39], v[64:65]
	v_pk_fma_f32 v[64:65], v[16:17], v[66:67], v[18:19]
	v_pk_fma_f32 v[66:67], v[20:21], v[66:67], v[22:23]
	v_add_f32_e32 v75, v64, v65
	v_add_f32_e32 v64, v66, v67
	v_pk_fma_f32 v[36:37], v[28:29], v[88:89], v[36:37] op_sel:[0,1,0]
	v_pk_fma_f32 v[38:39], v[30:31], v[88:89], v[38:39] op_sel:[0,1,0]
	v_add_f32_dpp v64, v64, v64 quad_perm:[1,0,3,2] row_mask:0xf bank_mask:0xf bound_ctrl:1
	ds_read_b128 v[4:7], v72 offset:12928
	ds_read_b128 v[16:19], v72 offset:13696
	v_add_f32_dpp v64, v64, v64 quad_perm:[2,3,0,1] row_mask:0xf bank_mask:0xf bound_ctrl:1
	ds_read_b128 v[20:23], v72 offset:14080
	ds_read_b128 v[28:31], v72 offset:14848
	v_add_f32_dpp v64, v64, v64 row_half_mirror row_mask:0xf bank_mask:0xf bound_ctrl:1
	s_nop 1
	v_add_f32_dpp v64, v64, v64 row_mirror row_mask:0xf bank_mask:0xf bound_ctrl:1
	v_pk_fma_f32 v[66:67], v[24:25], v[64:65], v[36:37] op_sel_hi:[1,0,1]
	v_pk_fma_f32 v[64:65], v[26:27], v[64:65], v[38:39] op_sel_hi:[1,0,1]
	v_pk_mul_f32 v[88:89], v[48:49], v[66:67]
	v_pk_mul_f32 v[34:35], v[34:35], v[64:65]
	v_pk_mul_f32 v[42:43], v[42:43], v[64:65]
	v_pk_fma_f32 v[96:97], v[32:33], v[66:67], v[34:35]
	v_pk_fma_f32 v[66:67], v[40:41], v[66:67], v[42:43]
	v_pk_mul_f32 v[64:65], v[50:51], v[64:65]
	v_add_f32_e32 v66, v66, v67
	v_pk_fma_f32 v[88:89], v[52:53], v[90:91], v[88:89] op_sel_hi:[1,0,1]
	v_pk_fma_f32 v[64:65], v[54:55], v[90:91], v[64:65] op_sel_hi:[1,0,1]
	v_add_f32_dpp v66, v66, v66 quad_perm:[1,0,3,2] row_mask:0xf bank_mask:0xf bound_ctrl:1
	v_add_f32_e32 v90, v96, v97
	v_add_f32_dpp v105, v75, v75 row_ror:8 row_mask:0xf bank_mask:0x3 bound_ctrl:1
	v_add_f32_dpp v66, v66, v66 quad_perm:[2,3,0,1] row_mask:0xf bank_mask:0xf bound_ctrl:1
	v_add_f32_dpp v107, v90, v90 row_ror:8 row_mask:0xf bank_mask:0x3 bound_ctrl:1
	ds_read_b128 v[24:27], v72 offset:14336
	ds_read_b128 v[36:39], v72 offset:14592
	v_add_f32_dpp v66, v66, v66 row_half_mirror row_mask:0xf bank_mask:0xf bound_ctrl:1
	ds_read_b128 v[48:51], v72 offset:16000
	ds_read_b128 v[32:35], v72 offset:15104
	v_add_f32_dpp v66, v66, v66 row_mirror row_mask:0xf bank_mask:0xf bound_ctrl:1
	v_pk_fma_f32 v[64:65], v[46:47], v[66:67], v[64:65] op_sel_hi:[1,0,1]
	v_pk_fma_f32 v[88:89], v[44:45], v[66:67], v[88:89] op_sel_hi:[1,0,1]
	s_waitcnt lgkmcnt(11)
	v_pk_mul_f32 v[66:67], v[94:95], v[64:65]
	v_pk_mul_f32 v[58:59], v[58:59], v[64:65]
	v_pk_fma_f32 v[66:67], v[92:93], v[88:89], v[66:67]
	v_pk_mul_f32 v[64:65], v[78:79], v[64:65]
	v_add_f32_e32 v66, v66, v67
	v_pk_fma_f32 v[78:79], v[56:57], v[88:89], v[58:59]
	v_pk_mul_f32 v[76:77], v[76:77], v[88:89]
	v_add_f32_dpp v66, v66, v66 quad_perm:[1,0,3,2] row_mask:0xf bank_mask:0xf bound_ctrl:1
	v_pk_fma_f32 v[64:65], v[98:99], v[82:83], v[64:65] op_sel_hi:[0,1,1]
	v_add_f32_e32 v104, v78, v79
	v_add_f32_dpp v66, v66, v66 quad_perm:[2,3,0,1] row_mask:0xf bank_mask:0xf bound_ctrl:1
	v_pk_fma_f32 v[76:77], v[98:99], v[80:81], v[76:77] op_sel_hi:[0,1,1]
	ds_read_b128 v[40:43], v72 offset:15488
	ds_read_b128 v[52:55], v72 offset:16256
	v_add_f32_dpp v66, v66, v66 row_half_mirror row_mask:0xf bank_mask:0xf bound_ctrl:1
	ds_read_b128 v[44:47], v72 offset:15744
	ds_read_b128 v[56:59], v72 offset:16512
	v_add_f32_dpp v78, v66, v66 row_mirror row_mask:0xf bank_mask:0xf bound_ctrl:1
	v_pk_fma_f32 v[64:65], v[62:63], v[78:79], v[64:65] op_sel_hi:[1,0,1]
	v_pk_fma_f32 v[66:67], v[60:61], v[78:79], v[76:77] op_sel_hi:[1,0,1]
	v_pk_mul_f32 v[102:103], v[86:87], v[64:65]
	v_pk_fma_f32 v[102:103], v[84:85], v[66:67], v[102:103]
	s_waitcnt lgkmcnt(14)
; template <int CTRL> DI float dppf(float v) { return __int_as_float(__builtin_amdgcn_update_dpp(0, __float_as_int(v), CTRL, 0xf, 0xf, false)); }
; DI float red16(float p) { p += dppf<0xB1>(p); p += dppf<0x4E>(p); p += dppf<0x141>(p); p += dppf<0x140>(p); return p; }
; DI void scan_task(const Params& P, int sb, unsigned char* lds) {
;     ...
;       for (int g4 = 0; g4 < CH / 4; ++g4) {
;         const float* gb = cb + g4 * 4 * SREC;
;         const float4 v4 = *(const float4*)(vrow + g4 * 4);
;         float pp[4];
; #pragma unroll
;         for (int i = 0; i < 4; ++i) {
;           ld_ops(nx3, gb + (i + 3) * SREC, q4);
;           const f2 a01 = {cur.a.x, cur.a.y}, a23 = {cur.a.z, cur.a.w}, w01 = {cur.w.x, cur.w.y}, w23 = {cur.w.z, cur.w.w};
;           const f2 k01 = {cur.k.x, cur.k.y}, k23 = {cur.k.z, cur.k.w}, b01 = {cur.b.x, cur.b.y}, b23 = {cur.b.z, cur.b.w};
;           const f2 r01 = {cur.r.x, cur.r.y}, r23 = {cur.r.z, cur.r.w};
;           f2 pa = S0 * a01; pa += S1 * a23;
;           const float vs = (i == 0) ? v4.x : (i == 1) ? v4.y : (i == 2) ? v4.z : v4.w;
;           const f2 vv = {vs, vs};
;           const f2 t0 = S0 * w01 + vv * k01, t1 = S1 * w23 + vv * k23;
;           const float sa = red16(pa.x + pa.y);
;           const f2 sa2 = {sa, sa};
;           S0 = t0 + sa2 * b01; S1 = t1 + sa2 * b23;
;           f2 py = S0 * r01; py += S1 * r23;
;           pp[i] = py.x + py.y;
;           cur = nxt; nxt = nx2; nx2 = nx3;
;         }
;         const float tA = o1 ? pp[0] : pp[1], kA = o1 ? pp[1] : pp[0];
;         const float tB = o1 ? pp[2] : pp[3], kB = o1 ? pp[3] : pp[2];
;         const float r0 = kA + dppf<0xB1>(tA), r1 = kB + dppf<0xB1>(tB);
;         const float tC = o2 ? r0 : r1, kC = o2 ? r1 : r0;
;         float u = kC + dppf<0x4E>(tC);
;         u += dppf<0x124>(u);
;         u += dppf<0x128>(u);
;         yb[(g4 * 4 + (q & 3)) * 16 + rowl] = u;
	v_pk_mul_f32 v[2:3], v[64:65], v[2:3]
	v_add_f32_e32 v102, v102, v103
	ds_read_b128 v[60:63], v72 offset:17152
	v_add_f32_dpp v105, v104, v104 row_ror:8 row_mask:0xf bank_mask:0xc bound_ctrl:1
	ds_read_b128 v[76:79], v72 offset:17408
	ds_read_b128 v[80:83], v72 offset:17664
	ds_read_b128 v[84:87], v72 offset:17920
	ds_read_b128 v[88:91], v100 offset:64
	ds_read_b128 v[92:95], v72 offset:16896
	v_add_f32_dpp v107, v102, v102 row_ror:8 row_mask:0xf bank_mask:0xc bound_ctrl:1
	v_pk_fma_f32 v[96:97], v[66:67], v[0:1], v[2:3]
	v_add_f32_dpp v108, v105, v105 row_half_mirror row_mask:0xf bank_mask:0x5 bound_ctrl:1
	v_add_f32_dpp v108, v107, v107 row_half_mirror row_mask:0xf bank_mask:0xa bound_ctrl:1
	ds_read_b128 v[0:3], v72 offset:18304
	v_add_f32_e32 v75, v96, v97
	s_waitcnt lgkmcnt(7)
	v_add_f32_dpp v108, v108, v108 quad_perm:[1,0,3,2] row_mask:0xf bank_mask:0xf bound_ctrl:1
	v_pk_mul_f32 v[14:15], v[14:15], v[112:113] op_sel_hi:[1,0]
	v_pk_mul_f32 v[12:13], v[12:13], v[112:113] op_sel_hi:[1,0]
	v_add_f32_dpp v108, v108, v108 quad_perm:[2,3,0,1] row_mask:0xf bank_mask:0xf bound_ctrl:1
	v_add_f32_dpp v75, v75, v75 quad_perm:[1,0,3,2] row_mask:0xf bank_mask:0xf bound_ctrl:1
	v_pk_fma_f32 v[64:65], v[64:65], v[10:11], v[14:15]
	v_pk_fma_f32 v[66:67], v[66:67], v[8:9], v[12:13]
	v_add_f32_dpp v75, v75, v75 quad_perm:[2,3,0,1] row_mask:0xf bank_mask:0xf bound_ctrl:1
	v_mov_b32_e32 v98, v115
	ds_write_b32 v73, v108 offset:512
	v_add_f32_dpp v75, v75, v75 row_half_mirror row_mask:0xf bank_mask:0xf bound_ctrl:1
	ds_read_b128 v[8:11], v72 offset:18816
	ds_read_b128 v[12:15], v72 offset:19072
	v_add_f32_dpp v96, v75, v75 row_mirror row_mask:0xf bank_mask:0xf bound_ctrl:1
	v_pk_fma_f32 v[64:65], v[6:7], v[96:97], v[64:65] op_sel_hi:[1,0,1]
	v_pk_fma_f32 v[66:67], v[4:5], v[96:97], v[66:67] op_sel_hi:[1,0,1]
	v_pk_mul_f32 v[18:19], v[18:19], v[64:65]
	v_pk_mul_f32 v[22:23], v[22:23], v[64:65]
	v_pk_mul_f32 v[36:37], v[36:37], v[66:67]
	v_pk_mul_f32 v[38:39], v[38:39], v[64:65]
	v_pk_fma_f32 v[64:65], v[16:17], v[66:67], v[18:19]
	v_pk_fma_f32 v[66:67], v[20:21], v[66:67], v[22:23]
	v_add_f32_e32 v75, v64, v65
	v_add_f32_e32 v64, v66, v67
	v_pk_fma_f32 v[36:37], v[28:29], v[112:113], v[36:37] op_sel:[0,1,0]
	v_pk_fma_f32 v[38:39], v[30:31], v[112:113], v[38:39] op_sel:[0,1,0]
	v_add_f32_dpp v64, v64, v64 quad_perm:[1,0,3,2] row_mask:0xf bank_mask:0xf bound_ctrl:1
	ds_read_b128 v[4:7], v72 offset:18560
	ds_read_b128 v[16:19], v72 offset:19328
	v_add_f32_dpp v64, v64, v64 quad_perm:[2,3,0,1] row_mask:0xf bank_mask:0xf bound_ctrl:1
	ds_read_b128 v[20:23], v72 offset:19712
	ds_read_b128 v[28:31], v72 offset:20480
	v_add_f32_dpp v64, v64, v64 row_half_mirror row_mask:0xf bank_mask:0xf bound_ctrl:1
	s_nop 1
	v_add_f32_dpp v64, v64, v64 row_mirror row_mask:0xf bank_mask:0xf bound_ctrl:1
	v_pk_fma_f32 v[66:67], v[24:25], v[64:65], v[36:37] op_sel_hi:[1,0,1]
	v_pk_fma_f32 v[64:65], v[26:27], v[64:65], v[38:39] op_sel_hi:[1,0,1]
	v_pk_mul_f32 v[112:113], v[48:49], v[66:67]
	v_pk_mul_f32 v[34:35], v[34:35], v[64:65]
	v_pk_mul_f32 v[42:43], v[42:43], v[64:65]
	v_pk_fma_f32 v[96:97], v[32:33], v[66:67], v[34:35]
	v_pk_fma_f32 v[66:67], v[40:41], v[66:67], v[42:43]
	v_pk_mul_f32 v[64:65], v[50:51], v[64:65]
	v_add_f32_e32 v66, v66, v67
	v_pk_fma_f32 v[112:113], v[52:53], v[114:115], v[112:113] op_sel_hi:[1,0,1]
	v_pk_fma_f32 v[64:65], v[54:55], v[114:115], v[64:65] op_sel_hi:[1,0,1]
	v_add_f32_dpp v66, v66, v66 quad_perm:[1,0,3,2] row_mask:0xf bank_mask:0xf bound_ctrl:1
	v_add_f32_e32 v114, v96, v97
	v_add_f32_dpp v105, v75, v75 row_ror:8 row_mask:0xf bank_mask:0x3 bound_ctrl:1
	v_add_f32_dpp v66, v66, v66 quad_perm:[2,3,0,1] row_mask:0xf bank_mask:0xf bound_ctrl:1
	v_add_f32_dpp v107, v114, v114 row_ror:8 row_mask:0xf bank_mask:0x3 bound_ctrl:1
	ds_read_b128 v[24:27], v72 offset:19968
	ds_read_b128 v[36:39], v72 offset:20224
	v_add_f32_dpp v66, v66, v66 row_half_mirror row_mask:0xf bank_mask:0xf bound_ctrl:1
	ds_read_b128 v[48:51], v72 offset:21632
	ds_read_b128 v[32:35], v72 offset:20736
	v_add_f32_dpp v66, v66, v66 row_mirror row_mask:0xf bank_mask:0xf bound_ctrl:1
	v_pk_fma_f32 v[64:65], v[46:47], v[66:67], v[64:65] op_sel_hi:[1,0,1]
	v_pk_fma_f32 v[112:113], v[44:45], v[66:67], v[112:113] op_sel_hi:[1,0,1]
	s_waitcnt lgkmcnt(11)
	v_pk_mul_f32 v[66:67], v[94:95], v[64:65]
	v_pk_mul_f32 v[58:59], v[58:59], v[64:65]
	v_pk_fma_f32 v[66:67], v[92:93], v[112:113], v[66:67]
	v_pk_mul_f32 v[64:65], v[78:79], v[64:65]
	v_add_f32_e32 v66, v66, v67
	v_pk_fma_f32 v[78:79], v[56:57], v[112:113], v[58:59]
	v_pk_mul_f32 v[76:77], v[76:77], v[112:113]
	v_add_f32_dpp v66, v66, v66 quad_perm:[1,0,3,2] row_mask:0xf bank_mask:0xf bound_ctrl:1
	v_pk_fma_f32 v[64:65], v[98:99], v[82:83], v[64:65] op_sel_hi:[0,1,1]
	v_add_f32_e32 v104, v78, v79
	v_add_f32_dpp v66, v66, v66 quad_perm:[2,3,0,1] row_mask:0xf bank_mask:0xf bound_ctrl:1
	v_pk_fma_f32 v[76:77], v[98:99], v[80:81], v[76:77] op_sel_hi:[0,1,1]
	ds_read_b128 v[40:43], v72 offset:21120
	ds_read_b128 v[52:55], v72 offset:21888
	v_add_f32_dpp v66, v66, v66 row_half_mirror row_mask:0xf bank_mask:0xf bound_ctrl:1
	ds_read_b128 v[44:47], v72 offset:21376
	ds_read_b128 v[56:59], v72 offset:22144
	v_add_f32_dpp v78, v66, v66 row_mirror row_mask:0xf bank_mask:0xf bound_ctrl:1
	v_pk_fma_f32 v[64:65], v[62:63], v[78:79], v[64:65] op_sel_hi:[1,0,1]
	v_pk_fma_f32 v[66:67], v[60:61], v[78:79], v[76:77] op_sel_hi:[1,0,1]
	v_pk_mul_f32 v[102:103], v[86:87], v[64:65]
	v_pk_fma_f32 v[102:103], v[84:85], v[66:67], v[102:103]
	s_waitcnt lgkmcnt(14)
; template <int CTRL> DI float dppf(float v) { return __int_as_float(__builtin_amdgcn_update_dpp(0, __float_as_int(v), CTRL, 0xf, 0xf, false)); }
; DI float red16(float p) { p += dppf<0xB1>(p); p += dppf<0x4E>(p); p += dppf<0x141>(p); p += dppf<0x140>(p); return p; }
; DI void scan_task(const Params& P, int sb, unsigned char* lds) {
;     ...
;       for (int g4 = 0; g4 < CH / 4; ++g4) {
;         const float* gb = cb + g4 * 4 * SREC;
;         const float4 v4 = *(const float4*)(vrow + g4 * 4);
;         float pp[4];
; #pragma unroll
;         for (int i = 0; i < 4; ++i) {
;           ld_ops(nx3, gb + (i + 3) * SREC, q4);
;           const f2 a01 = {cur.a.x, cur.a.y}, a23 = {cur.a.z, cur.a.w}, w01 = {cur.w.x, cur.w.y}, w23 = {cur.w.z, cur.w.w};
;           const f2 k01 = {cur.k.x, cur.k.y}, k23 = {cur.k.z, cur.k.w}, b01 = {cur.b.x, cur.b.y}, b23 = {cur.b.z, cur.b.w};
;           const f2 r01 = {cur.r.x, cur.r.y}, r23 = {cur.r.z, cur.r.w};
;           f2 pa = S0 * a01; pa += S1 * a23;
;           const float vs = (i == 0) ? v4.x : (i == 1) ? v4.y : (i == 2) ? v4.z : v4.w;
;           const f2 vv = {vs, vs};
;           const f2 t0 = S0 * w01 + vv * k01, t1 = S1 * w23 + vv * k23;
;           const float sa = red16(pa.x + pa.y);
;           const f2 sa2 = {sa, sa};
;           S0 = t0 + sa2 * b01; S1 = t1 + sa2 * b23;
;           f2 py = S0 * r01; py += S1 * r23;
;           pp[i] = py.x + py.y;
;           cur = nxt; nxt = nx2; nx2 = nx3;
;         }
;         const float tA = o1 ? pp[0] : pp[1], kA = o1 ? pp[1] : pp[0];
;         const float tB = o1 ? pp[2] : pp[3], kB = o1 ? pp[3] : pp[2];
;         const float r0 = kA + dppf<0xB1>(tA), r1 = kB + dppf<0xB1>(tB);
;         const float tC = o2 ? r0 : r1, kC = o2 ? r1 : r0;
;         float u = kC + dppf<0x4E>(tC);
;         u += dppf<0x124>(u);
;         u += dppf<0x128>(u);
;         yb[(g4 * 4 + (q & 3)) * 16 + rowl] = u;
	v_pk_mul_f32 v[2:3], v[64:65], v[2:3]
	v_add_f32_e32 v102, v102, v103
	ds_read_b128 v[60:63], v72 offset:22784
	v_add_f32_dpp v105, v104, v104 row_ror:8 row_mask:0xf bank_mask:0xc bound_ctrl:1
	ds_read_b128 v[76:79], v72 offset:23040
	ds_read_b128 v[80:83], v72 offset:23296
	ds_read_b128 v[84:87], v72 offset:23552
	ds_read_b128 v[112:115], v100 offset:80
	ds_read_b128 v[92:95], v72 offset:22528
	v_add_f32_dpp v107, v102, v102 row_ror:8 row_mask:0xf bank_mask:0xc bound_ctrl:1
	v_pk_fma_f32 v[96:97], v[66:67], v[0:1], v[2:3]
	v_add_f32_dpp v108, v105, v105 row_half_mirror row_mask:0xf bank_mask:0x5 bound_ctrl:1
	v_add_f32_dpp v108, v107, v107 row_half_mirror row_mask:0xf bank_mask:0xa bound_ctrl:1
	ds_read_b128 v[0:3], v72 offset:23936
	v_add_f32_e32 v75, v96, v97
	s_waitcnt lgkmcnt(7)
	v_add_f32_dpp v108, v108, v108 quad_perm:[1,0,3,2] row_mask:0xf bank_mask:0xf bound_ctrl:1
	v_pk_mul_f32 v[14:15], v[14:15], v[88:89] op_sel_hi:[1,0]
	v_pk_mul_f32 v[12:13], v[12:13], v[88:89] op_sel_hi:[1,0]
	v_add_f32_dpp v108, v108, v108 quad_perm:[2,3,0,1] row_mask:0xf bank_mask:0xf bound_ctrl:1
	v_add_f32_dpp v75, v75, v75 quad_perm:[1,0,3,2] row_mask:0xf bank_mask:0xf bound_ctrl:1
	v_pk_fma_f32 v[64:65], v[64:65], v[10:11], v[14:15]
	v_pk_fma_f32 v[66:67], v[66:67], v[8:9], v[12:13]
	v_add_f32_dpp v75, v75, v75 quad_perm:[2,3,0,1] row_mask:0xf bank_mask:0xf bound_ctrl:1
	v_mov_b32_e32 v98, v91
	ds_write_b32 v73, v108 offset:768
	v_add_f32_dpp v75, v75, v75 row_half_mirror row_mask:0xf bank_mask:0xf bound_ctrl:1
	ds_read_b128 v[8:11], v72 offset:24448
	ds_read_b128 v[12:15], v72 offset:24704
	v_add_f32_dpp v96, v75, v75 row_mirror row_mask:0xf bank_mask:0xf bound_ctrl:1
	v_pk_fma_f32 v[64:65], v[6:7], v[96:97], v[64:65] op_sel_hi:[1,0,1]
	v_pk_fma_f32 v[66:67], v[4:5], v[96:97], v[66:67] op_sel_hi:[1,0,1]
	v_pk_mul_f32 v[18:19], v[18:19], v[64:65]
	v_pk_mul_f32 v[22:23], v[22:23], v[64:65]
	v_pk_mul_f32 v[36:37], v[36:37], v[66:67]
	v_pk_mul_f32 v[38:39], v[38:39], v[64:65]
	v_pk_fma_f32 v[64:65], v[16:17], v[66:67], v[18:19]
	v_pk_fma_f32 v[66:67], v[20:21], v[66:67], v[22:23]
	v_add_f32_e32 v75, v64, v65
	v_add_f32_e32 v64, v66, v67
	v_pk_fma_f32 v[36:37], v[28:29], v[88:89], v[36:37] op_sel:[0,1,0]
	v_pk_fma_f32 v[38:39], v[30:31], v[88:89], v[38:39] op_sel:[0,1,0]
	v_add_f32_dpp v64, v64, v64 quad_perm:[1,0,3,2] row_mask:0xf bank_mask:0xf bound_ctrl:1
	ds_read_b128 v[4:7], v72 offset:24192
	ds_read_b128 v[16:19], v72 offset:24960
	v_add_f32_dpp v64, v64, v64 quad_perm:[2,3,0,1] row_mask:0xf bank_mask:0xf bound_ctrl:1
	ds_read_b128 v[20:23], v72 offset:25344
	ds_read_b128 v[28:31], v72 offset:26112
	v_add_f32_dpp v64, v64, v64 row_half_mirror row_mask:0xf bank_mask:0xf bound_ctrl:1
	s_nop 1
	v_add_f32_dpp v64, v64, v64 row_mirror row_mask:0xf bank_mask:0xf bound_ctrl:1
	v_pk_fma_f32 v[66:67], v[24:25], v[64:65], v[36:37] op_sel_hi:[1,0,1]
	v_pk_fma_f32 v[64:65], v[26:27], v[64:65], v[38:39] op_sel_hi:[1,0,1]
	v_pk_mul_f32 v[88:89], v[48:49], v[66:67]
	v_pk_mul_f32 v[34:35], v[34:35], v[64:65]
	v_pk_mul_f32 v[42:43], v[42:43], v[64:65]
	v_pk_fma_f32 v[96:97], v[32:33], v[66:67], v[34:35]
	v_pk_fma_f32 v[66:67], v[40:41], v[66:67], v[42:43]
	v_pk_mul_f32 v[64:65], v[50:51], v[64:65]
	v_add_f32_e32 v66, v66, v67
	v_pk_fma_f32 v[88:89], v[52:53], v[90:91], v[88:89] op_sel_hi:[1,0,1]
	v_pk_fma_f32 v[64:65], v[54:55], v[90:91], v[64:65] op_sel_hi:[1,0,1]
	v_add_f32_dpp v66, v66, v66 quad_perm:[1,0,3,2] row_mask:0xf bank_mask:0xf bound_ctrl:1
	v_add_f32_e32 v90, v96, v97
	v_add_f32_dpp v105, v75, v75 row_ror:8 row_mask:0xf bank_mask:0x3 bound_ctrl:1
	v_add_f32_dpp v66, v66, v66 quad_perm:[2,3,0,1] row_mask:0xf bank_mask:0xf bound_ctrl:1
	v_add_f32_dpp v107, v90, v90 row_ror:8 row_mask:0xf bank_mask:0x3 bound_ctrl:1
	ds_read_b128 v[24:27], v72 offset:25600
	ds_read_b128 v[36:39], v72 offset:25856
	v_add_f32_dpp v66, v66, v66 row_half_mirror row_mask:0xf bank_mask:0xf bound_ctrl:1
	ds_read_b128 v[48:51], v72 offset:27264
	ds_read_b128 v[32:35], v72 offset:26368
	v_add_f32_dpp v66, v66, v66 row_mirror row_mask:0xf bank_mask:0xf bound_ctrl:1
	v_pk_fma_f32 v[64:65], v[46:47], v[66:67], v[64:65] op_sel_hi:[1,0,1]
	v_pk_fma_f32 v[88:89], v[44:45], v[66:67], v[88:89] op_sel_hi:[1,0,1]
	s_waitcnt lgkmcnt(11)
	v_pk_mul_f32 v[66:67], v[94:95], v[64:65]
	v_pk_mul_f32 v[58:59], v[58:59], v[64:65]
	v_pk_fma_f32 v[66:67], v[92:93], v[88:89], v[66:67]
	v_pk_mul_f32 v[64:65], v[78:79], v[64:65]
	v_add_f32_e32 v66, v66, v67
	v_pk_fma_f32 v[78:79], v[56:57], v[88:89], v[58:59]
	v_pk_mul_f32 v[76:77], v[76:77], v[88:89]
	v_add_f32_dpp v66, v66, v66 quad_perm:[1,0,3,2] row_mask:0xf bank_mask:0xf bound_ctrl:1
	v_pk_fma_f32 v[64:65], v[98:99], v[82:83], v[64:65] op_sel_hi:[0,1,1]
	v_add_f32_e32 v104, v78, v79
	v_add_f32_dpp v66, v66, v66 quad_perm:[2,3,0,1] row_mask:0xf bank_mask:0xf bound_ctrl:1
	v_pk_fma_f32 v[76:77], v[98:99], v[80:81], v[76:77] op_sel_hi:[0,1,1]
	ds_read_b128 v[40:43], v72 offset:26752
	ds_read_b128 v[52:55], v72 offset:27520
	v_add_f32_dpp v66, v66, v66 row_half_mirror row_mask:0xf bank_mask:0xf bound_ctrl:1
	ds_read_b128 v[44:47], v72 offset:27008
	ds_read_b128 v[56:59], v72 offset:27776
	v_add_f32_dpp v78, v66, v66 row_mirror row_mask:0xf bank_mask:0xf bound_ctrl:1
	v_pk_fma_f32 v[64:65], v[62:63], v[78:79], v[64:65] op_sel_hi:[1,0,1]
	v_pk_fma_f32 v[66:67], v[60:61], v[78:79], v[76:77] op_sel_hi:[1,0,1]
	v_pk_mul_f32 v[102:103], v[86:87], v[64:65]
	v_pk_fma_f32 v[102:103], v[84:85], v[66:67], v[102:103]
	s_waitcnt lgkmcnt(14)
; template <int CTRL> DI float dppf(float v) { return __int_as_float(__builtin_amdgcn_update_dpp(0, __float_as_int(v), CTRL, 0xf, 0xf, false)); }
; DI float red16(float p) { p += dppf<0xB1>(p); p += dppf<0x4E>(p); p += dppf<0x141>(p); p += dppf<0x140>(p); return p; }
; DI void scan_task(const Params& P, int sb, unsigned char* lds) {
;     ...
;       for (int g4 = 0; g4 < CH / 4; ++g4) {
;         const float* gb = cb + g4 * 4 * SREC;
;         const float4 v4 = *(const float4*)(vrow + g4 * 4);
;         float pp[4];
; #pragma unroll
;         for (int i = 0; i < 4; ++i) {
;           ld_ops(nx3, gb + (i + 3) * SREC, q4);
;           const f2 a01 = {cur.a.x, cur.a.y}, a23 = {cur.a.z, cur.a.w}, w01 = {cur.w.x, cur.w.y}, w23 = {cur.w.z, cur.w.w};
;           const f2 k01 = {cur.k.x, cur.k.y}, k23 = {cur.k.z, cur.k.w}, b01 = {cur.b.x, cur.b.y}, b23 = {cur.b.z, cur.b.w};
;           const f2 r01 = {cur.r.x, cur.r.y}, r23 = {cur.r.z, cur.r.w};
;           f2 pa = S0 * a01; pa += S1 * a23;
;           const float vs = (i == 0) ? v4.x : (i == 1) ? v4.y : (i == 2) ? v4.z : v4.w;
;           const f2 vv = {vs, vs};
;           const f2 t0 = S0 * w01 + vv * k01, t1 = S1 * w23 + vv * k23;
;           const float sa = red16(pa.x + pa.y);
;           const f2 sa2 = {sa, sa};
;           S0 = t0 + sa2 * b01; S1 = t1 + sa2 * b23;
;           f2 py = S0 * r01; py += S1 * r23;
;           pp[i] = py.x + py.y;
;           cur = nxt; nxt = nx2; nx2 = nx3;
;         }
;         const float tA = o1 ? pp[0] : pp[1], kA = o1 ? pp[1] : pp[0];
;         const float tB = o1 ? pp[2] : pp[3], kB = o1 ? pp[3] : pp[2];
;         const float r0 = kA + dppf<0xB1>(tA), r1 = kB + dppf<0xB1>(tB);
;         const float tC = o2 ? r0 : r1, kC = o2 ? r1 : r0;
;         float u = kC + dppf<0x4E>(tC);
;         u += dppf<0x124>(u);
;         u += dppf<0x128>(u);
;         yb[(g4 * 4 + (q & 3)) * 16 + rowl] = u;
	v_pk_mul_f32 v[2:3], v[64:65], v[2:3]
	v_add_f32_e32 v102, v102, v103
	ds_read_b128 v[60:63], v72 offset:28416
	v_add_f32_dpp v105, v104, v104 row_ror:8 row_mask:0xf bank_mask:0xc bound_ctrl:1
	ds_read_b128 v[76:79], v72 offset:28672
	ds_read_b128 v[80:83], v72 offset:28928
	ds_read_b128 v[84:87], v72 offset:29184
	ds_read_b128 v[88:91], v100 offset:96
	ds_read_b128 v[92:95], v72 offset:28160
	v_add_f32_dpp v107, v102, v102 row_ror:8 row_mask:0xf bank_mask:0xc bound_ctrl:1
	v_pk_fma_f32 v[96:97], v[66:67], v[0:1], v[2:3]
	v_add_f32_dpp v108, v105, v105 row_half_mirror row_mask:0xf bank_mask:0x5 bound_ctrl:1
	v_add_f32_dpp v108, v107, v107 row_half_mirror row_mask:0xf bank_mask:0xa bound_ctrl:1
	ds_read_b128 v[0:3], v72 offset:29568
	v_add_f32_e32 v75, v96, v97
	s_waitcnt lgkmcnt(7)
	v_add_f32_dpp v108, v108, v108 quad_perm:[1,0,3,2] row_mask:0xf bank_mask:0xf bound_ctrl:1
	v_pk_mul_f32 v[14:15], v[14:15], v[112:113] op_sel_hi:[1,0]
	v_pk_mul_f32 v[12:13], v[12:13], v[112:113] op_sel_hi:[1,0]
	v_add_f32_dpp v108, v108, v108 quad_perm:[2,3,0,1] row_mask:0xf bank_mask:0xf bound_ctrl:1
	v_add_f32_dpp v75, v75, v75 quad_perm:[1,0,3,2] row_mask:0xf bank_mask:0xf bound_ctrl:1
	v_pk_fma_f32 v[64:65], v[64:65], v[10:11], v[14:15]
	v_pk_fma_f32 v[66:67], v[66:67], v[8:9], v[12:13]
	v_add_f32_dpp v75, v75, v75 quad_perm:[2,3,0,1] row_mask:0xf bank_mask:0xf bound_ctrl:1
	v_mov_b32_e32 v98, v115
	ds_write_b32 v73, v108 offset:1024
	v_add_f32_dpp v75, v75, v75 row_half_mirror row_mask:0xf bank_mask:0xf bound_ctrl:1
	ds_read_b128 v[8:11], v72 offset:30080
	ds_read_b128 v[12:15], v72 offset:30336
	v_add_f32_dpp v96, v75, v75 row_mirror row_mask:0xf bank_mask:0xf bound_ctrl:1
	v_pk_fma_f32 v[64:65], v[6:7], v[96:97], v[64:65] op_sel_hi:[1,0,1]
	v_pk_fma_f32 v[66:67], v[4:5], v[96:97], v[66:67] op_sel_hi:[1,0,1]
	v_pk_mul_f32 v[18:19], v[18:19], v[64:65]
	v_pk_mul_f32 v[22:23], v[22:23], v[64:65]
	v_pk_mul_f32 v[36:37], v[36:37], v[66:67]
	v_pk_mul_f32 v[38:39], v[38:39], v[64:65]
	v_pk_fma_f32 v[64:65], v[16:17], v[66:67], v[18:19]
	v_pk_fma_f32 v[66:67], v[20:21], v[66:67], v[22:23]
	v_add_f32_e32 v75, v64, v65
	v_add_f32_e32 v64, v66, v67
	v_pk_fma_f32 v[36:37], v[28:29], v[112:113], v[36:37] op_sel:[0,1,0]
	v_pk_fma_f32 v[38:39], v[30:31], v[112:113], v[38:39] op_sel:[0,1,0]
	v_add_f32_dpp v64, v64, v64 quad_perm:[1,0,3,2] row_mask:0xf bank_mask:0xf bound_ctrl:1
	ds_read_b128 v[4:7], v72 offset:29824
	ds_read_b128 v[16:19], v72 offset:30592
	v_add_f32_dpp v64, v64, v64 quad_perm:[2,3,0,1] row_mask:0xf bank_mask:0xf bound_ctrl:1
	ds_read_b128 v[20:23], v72 offset:30976
	ds_read_b128 v[28:31], v72 offset:31744
	v_add_f32_dpp v64, v64, v64 row_half_mirror row_mask:0xf bank_mask:0xf bound_ctrl:1
	s_nop 1
	v_add_f32_dpp v64, v64, v64 row_mirror row_mask:0xf bank_mask:0xf bound_ctrl:1
	v_pk_fma_f32 v[66:67], v[24:25], v[64:65], v[36:37] op_sel_hi:[1,0,1]
	v_pk_fma_f32 v[64:65], v[26:27], v[64:65], v[38:39] op_sel_hi:[1,0,1]
	v_pk_mul_f32 v[112:113], v[48:49], v[66:67]
	v_pk_mul_f32 v[34:35], v[34:35], v[64:65]
	v_pk_mul_f32 v[42:43], v[42:43], v[64:65]
	v_pk_fma_f32 v[96:97], v[32:33], v[66:67], v[34:35]
	v_pk_fma_f32 v[66:67], v[40:41], v[66:67], v[42:43]
	v_pk_mul_f32 v[64:65], v[50:51], v[64:65]
	v_add_f32_e32 v66, v66, v67
	v_pk_fma_f32 v[112:113], v[52:53], v[114:115], v[112:113] op_sel_hi:[1,0,1]
	v_pk_fma_f32 v[64:65], v[54:55], v[114:115], v[64:65] op_sel_hi:[1,0,1]
	v_add_f32_dpp v66, v66, v66 quad_perm:[1,0,3,2] row_mask:0xf bank_mask:0xf bound_ctrl:1
	v_add_f32_e32 v114, v96, v97
	v_add_f32_dpp v105, v75, v75 row_ror:8 row_mask:0xf bank_mask:0x3 bound_ctrl:1
	v_add_f32_dpp v66, v66, v66 quad_perm:[2,3,0,1] row_mask:0xf bank_mask:0xf bound_ctrl:1
	v_add_f32_dpp v107, v114, v114 row_ror:8 row_mask:0xf bank_mask:0x3 bound_ctrl:1
	ds_read_b128 v[24:27], v72 offset:31232
	ds_read_b128 v[36:39], v72 offset:31488
	v_add_f32_dpp v66, v66, v66 row_half_mirror row_mask:0xf bank_mask:0xf bound_ctrl:1
	ds_read_b128 v[48:51], v72 offset:32896
	ds_read_b128 v[32:35], v72 offset:32000
	v_add_f32_dpp v66, v66, v66 row_mirror row_mask:0xf bank_mask:0xf bound_ctrl:1
	v_pk_fma_f32 v[64:65], v[46:47], v[66:67], v[64:65] op_sel_hi:[1,0,1]
	v_pk_fma_f32 v[112:113], v[44:45], v[66:67], v[112:113] op_sel_hi:[1,0,1]
	s_waitcnt lgkmcnt(11)
	v_pk_mul_f32 v[66:67], v[94:95], v[64:65]
	v_pk_mul_f32 v[58:59], v[58:59], v[64:65]
	v_pk_fma_f32 v[66:67], v[92:93], v[112:113], v[66:67]
	v_pk_mul_f32 v[64:65], v[78:79], v[64:65]
	v_add_f32_e32 v66, v66, v67
	v_pk_fma_f32 v[78:79], v[56:57], v[112:113], v[58:59]
	v_pk_mul_f32 v[76:77], v[76:77], v[112:113]
	v_add_f32_dpp v66, v66, v66 quad_perm:[1,0,3,2] row_mask:0xf bank_mask:0xf bound_ctrl:1
	v_pk_fma_f32 v[64:65], v[98:99], v[82:83], v[64:65] op_sel_hi:[0,1,1]
	v_add_f32_e32 v104, v78, v79
	v_add_f32_dpp v66, v66, v66 quad_perm:[2,3,0,1] row_mask:0xf bank_mask:0xf bound_ctrl:1
	v_pk_fma_f32 v[76:77], v[98:99], v[80:81], v[76:77] op_sel_hi:[0,1,1]
	ds_read_b128 v[40:43], v72 offset:32384
	ds_read_b128 v[52:55], v72 offset:33152
	v_add_f32_dpp v66, v66, v66 row_half_mirror row_mask:0xf bank_mask:0xf bound_ctrl:1
	ds_read_b128 v[44:47], v72 offset:32640
	ds_read_b128 v[56:59], v72 offset:33408
	v_add_f32_dpp v78, v66, v66 row_mirror row_mask:0xf bank_mask:0xf bound_ctrl:1
	v_pk_fma_f32 v[64:65], v[62:63], v[78:79], v[64:65] op_sel_hi:[1,0,1]
	v_pk_fma_f32 v[66:67], v[60:61], v[78:79], v[76:77] op_sel_hi:[1,0,1]
	v_pk_mul_f32 v[102:103], v[86:87], v[64:65]
	v_pk_fma_f32 v[102:103], v[84:85], v[66:67], v[102:103]
	s_waitcnt lgkmcnt(14)
; template <int CTRL> DI float dppf(float v) { return __int_as_float(__builtin_amdgcn_update_dpp(0, __float_as_int(v), CTRL, 0xf, 0xf, false)); }
; DI float red16(float p) { p += dppf<0xB1>(p); p += dppf<0x4E>(p); p += dppf<0x141>(p); p += dppf<0x140>(p); return p; }
; DI void scan_task(const Params& P, int sb, unsigned char* lds) {
;     ...
;       for (int g4 = 0; g4 < CH / 4; ++g4) {
;         const float* gb = cb + g4 * 4 * SREC;
;         const float4 v4 = *(const float4*)(vrow + g4 * 4);
;         float pp[4];
; #pragma unroll
;         for (int i = 0; i < 4; ++i) {
;           ld_ops(nx3, gb + (i + 3) * SREC, q4);
;           const f2 a01 = {cur.a.x, cur.a.y}, a23 = {cur.a.z, cur.a.w}, w01 = {cur.w.x, cur.w.y}, w23 = {cur.w.z, cur.w.w};
;           const f2 k01 = {cur.k.x, cur.k.y}, k23 = {cur.k.z, cur.k.w}, b01 = {cur.b.x, cur.b.y}, b23 = {cur.b.z, cur.b.w};
;           const f2 r01 = {cur.r.x, cur.r.y}, r23 = {cur.r.z, cur.r.w};
;           f2 pa = S0 * a01; pa += S1 * a23;
;           const float vs = (i == 0) ? v4.x : (i == 1) ? v4.y : (i == 2) ? v4.z : v4.w;
;           const f2 vv = {vs, vs};
;           const f2 t0 = S0 * w01 + vv * k01, t1 = S1 * w23 + vv * k23;
;           const float sa = red16(pa.x + pa.y);
;           const f2 sa2 = {sa, sa};
;           S0 = t0 + sa2 * b01; S1 = t1 + sa2 * b23;
;           f2 py = S0 * r01; py += S1 * r23;
;           pp[i] = py.x + py.y;
;           cur = nxt; nxt = nx2; nx2 = nx3;
;         }
;         const float tA = o1 ? pp[0] : pp[1], kA = o1 ? pp[1] : pp[0];
;         const float tB = o1 ? pp[2] : pp[3], kB = o1 ? pp[3] : pp[2];
;         const float r0 = kA + dppf<0xB1>(tA), r1 = kB + dppf<0xB1>(tB);
;         const float tC = o2 ? r0 : r1, kC = o2 ? r1 : r0;
;         float u = kC + dppf<0x4E>(tC);
;         u += dppf<0x124>(u);
;         u += dppf<0x128>(u);
;         yb[(g4 * 4 + (q & 3)) * 16 + rowl] = u;
	v_pk_mul_f32 v[2:3], v[64:65], v[2:3]
	v_add_f32_e32 v102, v102, v103
	ds_read_b128 v[60:63], v72 offset:34048
	v_add_f32_dpp v105, v104, v104 row_ror:8 row_mask:0xf bank_mask:0xc bound_ctrl:1
	ds_read_b128 v[76:79], v72 offset:34304
	ds_read_b128 v[80:83], v72 offset:34560
	ds_read_b128 v[84:87], v72 offset:34816
	ds_read_b128 v[112:115], v100 offset:112
	ds_read_b128 v[92:95], v72 offset:33792
	v_add_f32_dpp v107, v102, v102 row_ror:8 row_mask:0xf bank_mask:0xc bound_ctrl:1
	v_pk_fma_f32 v[96:97], v[66:67], v[0:1], v[2:3]
	v_add_f32_dpp v108, v105, v105 row_half_mirror row_mask:0xf bank_mask:0x5 bound_ctrl:1
	v_add_f32_dpp v108, v107, v107 row_half_mirror row_mask:0xf bank_mask:0xa bound_ctrl:1
	ds_read_b128 v[0:3], v72 offset:35200
	v_add_f32_e32 v75, v96, v97
	s_waitcnt lgkmcnt(7)
	v_add_f32_dpp v108, v108, v108 quad_perm:[1,0,3,2] row_mask:0xf bank_mask:0xf bound_ctrl:1
	v_pk_mul_f32 v[14:15], v[14:15], v[88:89] op_sel_hi:[1,0]
	v_pk_mul_f32 v[12:13], v[12:13], v[88:89] op_sel_hi:[1,0]
	v_add_f32_dpp v108, v108, v108 quad_perm:[2,3,0,1] row_mask:0xf bank_mask:0xf bound_ctrl:1
	v_add_f32_dpp v75, v75, v75 quad_perm:[1,0,3,2] row_mask:0xf bank_mask:0xf bound_ctrl:1
	v_pk_fma_f32 v[64:65], v[64:65], v[10:11], v[14:15]
	v_pk_fma_f32 v[66:67], v[66:67], v[8:9], v[12:13]
	v_add_f32_dpp v75, v75, v75 quad_perm:[2,3,0,1] row_mask:0xf bank_mask:0xf bound_ctrl:1
	v_mov_b32_e32 v98, v91
	ds_write_b32 v73, v108 offset:1280
	v_add_f32_dpp v75, v75, v75 row_half_mirror row_mask:0xf bank_mask:0xf bound_ctrl:1
	ds_read_b128 v[8:11], v72 offset:35712
	ds_read_b128 v[12:15], v72 offset:35968
	v_add_f32_dpp v96, v75, v75 row_mirror row_mask:0xf bank_mask:0xf bound_ctrl:1
	v_pk_fma_f32 v[64:65], v[6:7], v[96:97], v[64:65] op_sel_hi:[1,0,1]
	v_pk_fma_f32 v[66:67], v[4:5], v[96:97], v[66:67] op_sel_hi:[1,0,1]
	v_pk_mul_f32 v[18:19], v[18:19], v[64:65]
	v_pk_mul_f32 v[22:23], v[22:23], v[64:65]
	v_pk_mul_f32 v[36:37], v[36:37], v[66:67]
	v_pk_mul_f32 v[38:39], v[38:39], v[64:65]
	v_pk_fma_f32 v[64:65], v[16:17], v[66:67], v[18:19]
	v_pk_fma_f32 v[66:67], v[20:21], v[66:67], v[22:23]
	v_add_f32_e32 v75, v64, v65
	v_add_f32_e32 v64, v66, v67
	v_pk_fma_f32 v[36:37], v[28:29], v[88:89], v[36:37] op_sel:[0,1,0]
	v_pk_fma_f32 v[38:39], v[30:31], v[88:89], v[38:39] op_sel:[0,1,0]
	v_add_f32_dpp v64, v64, v64 quad_perm:[1,0,3,2] row_mask:0xf bank_mask:0xf bound_ctrl:1
	ds_read_b128 v[4:7], v72 offset:35456
	ds_read_b128 v[16:19], v72 offset:36224
	v_add_f32_dpp v64, v64, v64 quad_perm:[2,3,0,1] row_mask:0xf bank_mask:0xf bound_ctrl:1
	ds_read_b128 v[20:23], v72 offset:36608
	ds_read_b128 v[28:31], v72 offset:37376
	v_add_f32_dpp v64, v64, v64 row_half_mirror row_mask:0xf bank_mask:0xf bound_ctrl:1
	s_nop 1
	v_add_f32_dpp v64, v64, v64 row_mirror row_mask:0xf bank_mask:0xf bound_ctrl:1
	v_pk_fma_f32 v[66:67], v[24:25], v[64:65], v[36:37] op_sel_hi:[1,0,1]
	v_pk_fma_f32 v[64:65], v[26:27], v[64:65], v[38:39] op_sel_hi:[1,0,1]
	v_pk_mul_f32 v[88:89], v[48:49], v[66:67]
	v_pk_mul_f32 v[34:35], v[34:35], v[64:65]
	v_pk_mul_f32 v[42:43], v[42:43], v[64:65]
	v_pk_fma_f32 v[96:97], v[32:33], v[66:67], v[34:35]
	v_pk_fma_f32 v[66:67], v[40:41], v[66:67], v[42:43]
	v_pk_mul_f32 v[64:65], v[50:51], v[64:65]
	v_add_f32_e32 v66, v66, v67
	v_pk_fma_f32 v[88:89], v[52:53], v[90:91], v[88:89] op_sel_hi:[1,0,1]
	v_pk_fma_f32 v[64:65], v[54:55], v[90:91], v[64:65] op_sel_hi:[1,0,1]
	v_add_f32_dpp v66, v66, v66 quad_perm:[1,0,3,2] row_mask:0xf bank_mask:0xf bound_ctrl:1
	v_add_f32_e32 v90, v96, v97
	v_add_f32_dpp v105, v75, v75 row_ror:8 row_mask:0xf bank_mask:0x3 bound_ctrl:1
	v_add_f32_dpp v66, v66, v66 quad_perm:[2,3,0,1] row_mask:0xf bank_mask:0xf bound_ctrl:1
	v_add_f32_dpp v107, v90, v90 row_ror:8 row_mask:0xf bank_mask:0x3 bound_ctrl:1
	ds_read_b128 v[24:27], v72 offset:36864
	ds_read_b128 v[36:39], v72 offset:37120
	v_add_f32_dpp v66, v66, v66 row_half_mirror row_mask:0xf bank_mask:0xf bound_ctrl:1
	ds_read_b128 v[48:51], v72 offset:38528
	ds_read_b128 v[32:35], v72 offset:37632
	v_add_f32_dpp v66, v66, v66 row_mirror row_mask:0xf bank_mask:0xf bound_ctrl:1
	v_pk_fma_f32 v[64:65], v[46:47], v[66:67], v[64:65] op_sel_hi:[1,0,1]
	v_pk_fma_f32 v[88:89], v[44:45], v[66:67], v[88:89] op_sel_hi:[1,0,1]
	s_waitcnt lgkmcnt(11)
	v_pk_mul_f32 v[66:67], v[94:95], v[64:65]
	v_pk_mul_f32 v[58:59], v[58:59], v[64:65]
	v_pk_fma_f32 v[66:67], v[92:93], v[88:89], v[66:67]
	v_pk_mul_f32 v[64:65], v[78:79], v[64:65]
	v_add_f32_e32 v66, v66, v67
	v_pk_fma_f32 v[78:79], v[56:57], v[88:89], v[58:59]
	v_pk_mul_f32 v[76:77], v[76:77], v[88:89]
	v_add_f32_dpp v66, v66, v66 quad_perm:[1,0,3,2] row_mask:0xf bank_mask:0xf bound_ctrl:1
	v_pk_fma_f32 v[64:65], v[98:99], v[82:83], v[64:65] op_sel_hi:[0,1,1]
	v_add_f32_e32 v104, v78, v79
	v_add_f32_dpp v66, v66, v66 quad_perm:[2,3,0,1] row_mask:0xf bank_mask:0xf bound_ctrl:1
	v_pk_fma_f32 v[76:77], v[98:99], v[80:81], v[76:77] op_sel_hi:[0,1,1]
	ds_read_b128 v[40:43], v72 offset:38016
	ds_read_b128 v[52:55], v72 offset:38784
	v_add_f32_dpp v66, v66, v66 row_half_mirror row_mask:0xf bank_mask:0xf bound_ctrl:1
	ds_read_b128 v[44:47], v72 offset:38272
	ds_read_b128 v[56:59], v72 offset:39040
	v_add_f32_dpp v78, v66, v66 row_mirror row_mask:0xf bank_mask:0xf bound_ctrl:1
	v_pk_fma_f32 v[64:65], v[62:63], v[78:79], v[64:65] op_sel_hi:[1,0,1]
	v_pk_fma_f32 v[66:67], v[60:61], v[78:79], v[76:77] op_sel_hi:[1,0,1]
	v_pk_mul_f32 v[102:103], v[86:87], v[64:65]
	v_pk_fma_f32 v[102:103], v[84:85], v[66:67], v[102:103]
	s_waitcnt lgkmcnt(14)
; template <int CTRL> DI float dppf(float v) { return __int_as_float(__builtin_amdgcn_update_dpp(0, __float_as_int(v), CTRL, 0xf, 0xf, false)); }
; DI float red16(float p) { p += dppf<0xB1>(p); p += dppf<0x4E>(p); p += dppf<0x141>(p); p += dppf<0x140>(p); return p; }
; DI void scan_task(const Params& P, int sb, unsigned char* lds) {
;     ...
;       for (int g4 = 0; g4 < CH / 4; ++g4) {
;         const float* gb = cb + g4 * 4 * SREC;
;         const float4 v4 = *(const float4*)(vrow + g4 * 4);
;         float pp[4];
; #pragma unroll
;         for (int i = 0; i < 4; ++i) {
;           ld_ops(nx3, gb + (i + 3) * SREC, q4);
;           const f2 a01 = {cur.a.x, cur.a.y}, a23 = {cur.a.z, cur.a.w}, w01 = {cur.w.x, cur.w.y}, w23 = {cur.w.z, cur.w.w};
;           const f2 k01 = {cur.k.x, cur.k.y}, k23 = {cur.k.z, cur.k.w}, b01 = {cur.b.x, cur.b.y}, b23 = {cur.b.z, cur.b.w};
;           const f2 r01 = {cur.r.x, cur.r.y}, r23 = {cur.r.z, cur.r.w};
;           f2 pa = S0 * a01; pa += S1 * a23;
;           const float vs = (i == 0) ? v4.x : (i == 1) ? v4.y : (i == 2) ? v4.z : v4.w;
;           const f2 vv = {vs, vs};
;           const f2 t0 = S0 * w01 + vv * k01, t1 = S1 * w23 + vv * k23;
;           const float sa = red16(pa.x + pa.y);
;           const f2 sa2 = {sa, sa};
;           S0 = t0 + sa2 * b01; S1 = t1 + sa2 * b23;
;           f2 py = S0 * r01; py += S1 * r23;
;           pp[i] = py.x + py.y;
;           cur = nxt; nxt = nx2; nx2 = nx3;
;         }
;         const float tA = o1 ? pp[0] : pp[1], kA = o1 ? pp[1] : pp[0];
;         const float tB = o1 ? pp[2] : pp[3], kB = o1 ? pp[3] : pp[2];
;         const float r0 = kA + dppf<0xB1>(tA), r1 = kB + dppf<0xB1>(tB);
;         const float tC = o2 ? r0 : r1, kC = o2 ? r1 : r0;
;         float u = kC + dppf<0x4E>(tC);
;         u += dppf<0x124>(u);
;         u += dppf<0x128>(u);
;         yb[(g4 * 4 + (q & 3)) * 16 + rowl] = u;
;       }
;       __syncthreads();
	v_pk_mul_f32 v[2:3], v[64:65], v[2:3]
	v_add_f32_e32 v102, v102, v103
	ds_read_b128 v[60:63], v72 offset:39680
	v_add_f32_dpp v105, v104, v104 row_ror:8 row_mask:0xf bank_mask:0xc bound_ctrl:1
	ds_read_b128 v[76:79], v72 offset:39936
	ds_read_b128 v[80:83], v72 offset:40192
	ds_read_b128 v[84:87], v72 offset:40448
	ds_read_b128 v[92:95], v72 offset:39424
	v_add_f32_dpp v107, v102, v102 row_ror:8 row_mask:0xf bank_mask:0xc bound_ctrl:1
	v_pk_fma_f32 v[96:97], v[66:67], v[0:1], v[2:3]
	v_add_f32_dpp v108, v105, v105 row_half_mirror row_mask:0xf bank_mask:0x5 bound_ctrl:1
	v_add_f32_dpp v108, v107, v107 row_half_mirror row_mask:0xf bank_mask:0xa bound_ctrl:1
	ds_read_b128 v[0:3], v72 offset:40832
	v_add_f32_e32 v75, v96, v97
	s_waitcnt lgkmcnt(6)
	v_add_f32_dpp v108, v108, v108 quad_perm:[1,0,3,2] row_mask:0xf bank_mask:0xf bound_ctrl:1
	v_pk_mul_f32 v[14:15], v[14:15], v[112:113] op_sel_hi:[1,0]
	v_pk_mul_f32 v[12:13], v[12:13], v[112:113] op_sel_hi:[1,0]
	v_add_f32_dpp v108, v108, v108 quad_perm:[2,3,0,1] row_mask:0xf bank_mask:0xf bound_ctrl:1
	v_add_f32_dpp v75, v75, v75 quad_perm:[1,0,3,2] row_mask:0xf bank_mask:0xf bound_ctrl:1
	v_pk_fma_f32 v[64:65], v[64:65], v[10:11], v[14:15]
	v_pk_fma_f32 v[66:67], v[66:67], v[8:9], v[12:13]
	v_add_f32_dpp v75, v75, v75 quad_perm:[2,3,0,1] row_mask:0xf bank_mask:0xf bound_ctrl:1
	v_mov_b32_e32 v98, v115
	ds_write_b32 v73, v108 offset:1536
	v_add_f32_dpp v75, v75, v75 row_half_mirror row_mask:0xf bank_mask:0xf bound_ctrl:1
	ds_read_b128 v[8:11], v72 offset:41344
	ds_read_b128 v[12:15], v72 offset:41600
	v_add_f32_dpp v96, v75, v75 row_mirror row_mask:0xf bank_mask:0xf bound_ctrl:1
	v_pk_fma_f32 v[64:65], v[6:7], v[96:97], v[64:65] op_sel_hi:[1,0,1]
	v_pk_fma_f32 v[66:67], v[4:5], v[96:97], v[66:67] op_sel_hi:[1,0,1]
	v_pk_mul_f32 v[18:19], v[18:19], v[64:65]
	v_pk_mul_f32 v[22:23], v[22:23], v[64:65]
	v_pk_mul_f32 v[36:37], v[36:37], v[66:67]
	v_pk_mul_f32 v[38:39], v[38:39], v[64:65]
	v_pk_fma_f32 v[64:65], v[16:17], v[66:67], v[18:19]
	v_pk_fma_f32 v[66:67], v[20:21], v[66:67], v[22:23]
	v_add_f32_e32 v75, v64, v65
	v_add_f32_e32 v64, v66, v67
	v_pk_fma_f32 v[36:37], v[28:29], v[112:113], v[36:37] op_sel:[0,1,0]
	v_pk_fma_f32 v[38:39], v[30:31], v[112:113], v[38:39] op_sel:[0,1,0]
	v_add_f32_dpp v64, v64, v64 quad_perm:[1,0,3,2] row_mask:0xf bank_mask:0xf bound_ctrl:1
	ds_read_b128 v[4:7], v72 offset:41088
	ds_read_b128 v[16:19], v72 offset:41856
	v_add_f32_dpp v64, v64, v64 quad_perm:[2,3,0,1] row_mask:0xf bank_mask:0xf bound_ctrl:1
	ds_read_b128 v[20:23], v72 offset:42240
	ds_read_b128 v[28:31], v72 offset:43008
	v_add_f32_dpp v64, v64, v64 row_half_mirror row_mask:0xf bank_mask:0xf bound_ctrl:1
	s_nop 1
	v_add_f32_dpp v64, v64, v64 row_mirror row_mask:0xf bank_mask:0xf bound_ctrl:1
	v_pk_fma_f32 v[66:67], v[24:25], v[64:65], v[36:37] op_sel_hi:[1,0,1]
	v_pk_fma_f32 v[64:65], v[26:27], v[64:65], v[38:39] op_sel_hi:[1,0,1]
	v_pk_mul_f32 v[112:113], v[48:49], v[66:67]
	v_pk_mul_f32 v[34:35], v[34:35], v[64:65]
	v_pk_mul_f32 v[42:43], v[42:43], v[64:65]
	v_pk_fma_f32 v[96:97], v[32:33], v[66:67], v[34:35]
	v_pk_fma_f32 v[66:67], v[40:41], v[66:67], v[42:43]
	v_pk_mul_f32 v[64:65], v[50:51], v[64:65]
	v_add_f32_e32 v66, v66, v67
	v_pk_fma_f32 v[112:113], v[52:53], v[114:115], v[112:113] op_sel_hi:[1,0,1]
	v_pk_fma_f32 v[64:65], v[54:55], v[114:115], v[64:65] op_sel_hi:[1,0,1]
	v_add_f32_dpp v66, v66, v66 quad_perm:[1,0,3,2] row_mask:0xf bank_mask:0xf bound_ctrl:1
	v_add_f32_e32 v114, v96, v97
	v_add_f32_dpp v105, v75, v75 row_ror:8 row_mask:0xf bank_mask:0x3 bound_ctrl:1
	v_add_f32_dpp v66, v66, v66 quad_perm:[2,3,0,1] row_mask:0xf bank_mask:0xf bound_ctrl:1
	v_add_f32_dpp v107, v114, v114 row_ror:8 row_mask:0xf bank_mask:0x3 bound_ctrl:1
	ds_read_b128 v[24:27], v72 offset:42496
	ds_read_b128 v[36:39], v72 offset:42752
	v_add_f32_dpp v66, v66, v66 row_half_mirror row_mask:0xf bank_mask:0xf bound_ctrl:1
	ds_read_b128 v[48:51], v72 offset:44160
	ds_read_b128 v[32:35], v72 offset:43264
	v_add_f32_dpp v66, v66, v66 row_mirror row_mask:0xf bank_mask:0xf bound_ctrl:1
	v_pk_fma_f32 v[64:65], v[46:47], v[66:67], v[64:65] op_sel_hi:[1,0,1]
	v_pk_fma_f32 v[112:113], v[44:45], v[66:67], v[112:113] op_sel_hi:[1,0,1]
	s_waitcnt lgkmcnt(11)
	v_pk_mul_f32 v[66:67], v[94:95], v[64:65]
	v_pk_mul_f32 v[58:59], v[58:59], v[64:65]
	v_pk_fma_f32 v[66:67], v[92:93], v[112:113], v[66:67]
	v_pk_mul_f32 v[64:65], v[78:79], v[64:65]
	v_add_f32_e32 v66, v66, v67
	v_pk_fma_f32 v[78:79], v[56:57], v[112:113], v[58:59]
	v_pk_mul_f32 v[76:77], v[76:77], v[112:113]
	v_add_f32_dpp v66, v66, v66 quad_perm:[1,0,3,2] row_mask:0xf bank_mask:0xf bound_ctrl:1
	v_pk_fma_f32 v[64:65], v[98:99], v[82:83], v[64:65] op_sel_hi:[0,1,1]
	v_add_f32_e32 v104, v78, v79
	v_add_f32_dpp v66, v66, v66 quad_perm:[2,3,0,1] row_mask:0xf bank_mask:0xf bound_ctrl:1
	v_pk_fma_f32 v[76:77], v[98:99], v[80:81], v[76:77] op_sel_hi:[0,1,1]
	ds_read_b128 v[40:43], v72 offset:43648
	ds_read_b128 v[52:55], v72 offset:44416
	v_add_f32_dpp v66, v66, v66 row_half_mirror row_mask:0xf bank_mask:0xf bound_ctrl:1
	ds_read_b128 v[44:47], v72 offset:43904
	ds_read_b128 v[56:59], v72 offset:44672
	v_add_f32_dpp v78, v66, v66 row_mirror row_mask:0xf bank_mask:0xf bound_ctrl:1
	v_pk_fma_f32 v[64:65], v[62:63], v[78:79], v[64:65] op_sel_hi:[1,0,1]
	v_pk_fma_f32 v[66:67], v[60:61], v[78:79], v[76:77] op_sel_hi:[1,0,1]
	v_pk_mul_f32 v[102:103], v[86:87], v[64:65]
	v_pk_fma_f32 v[102:103], v[84:85], v[66:67], v[102:103]
	s_nop 0
	v_add_f32_e32 v102, v102, v103
	v_add_f32_dpp v105, v104, v104 row_ror:8 row_mask:0xf bank_mask:0xc bound_ctrl:1
	s_nop 1
	v_add_f32_dpp v107, v102, v102 row_ror:8 row_mask:0xf bank_mask:0xc bound_ctrl:1
	v_add_f32_dpp v108, v105, v105 row_half_mirror row_mask:0xf bank_mask:0x5 bound_ctrl:1
	s_nop 1
	v_add_f32_dpp v108, v107, v107 row_half_mirror row_mask:0xf bank_mask:0xa bound_ctrl:1
	s_nop 1
	v_add_f32_dpp v108, v108, v108 quad_perm:[1,0,3,2] row_mask:0xf bank_mask:0xf bound_ctrl:1
	s_nop 1
	v_add_f32_dpp v108, v108, v108 quad_perm:[2,3,0,1] row_mask:0xf bank_mask:0xf bound_ctrl:1
	ds_write_b32 v73, v108 offset:1792
	s_add_i32 s0, s0, 1
	s_xor_b64 s[6:7], s[6:7], -1
	s_cmpk_eq_i32 s0, 0x108
	s_waitcnt lgkmcnt(0)
	s_barrier
	s_cbranch_scc0 .LBB0_1197
	s_mov_b64 s[4:5], 0
